# P9 split: rounds 0-1, seam, round 2 on half the CUs beside final RMSNorm of finished tiles on the other half (hand-written, nt)
# baseline (speedup 1.0000x reference)
_ZN2pb8mega_fwdENS_4ArgsE:
	s_load_dwordx8 s[4:11], s[0:1], 0xc0
	s_load_dwordx4 s[76:79], s[0:1], 0xe0
	s_load_dwordx2 s[82:83], s[0:1], 0xf0
	s_load_dword s33, s[0:1], 0x100
	v_and_b32_e32 v210, 0x3ff, v0
	s_mov_b32 s91, s2
	s_mov_b32 s101, s2
	s_mov_b32 s100, 0
	v_readfirstlane_b32 s3, v210
	s_waitcnt lgkmcnt(0)
	v_writelane_b32 v254, s4, 0
	s_nop 1
	v_writelane_b32 v254, s5, 1
	v_writelane_b32 v254, s6, 2
	v_writelane_b32 v254, s7, 3
	v_writelane_b32 v254, s8, 4
	v_writelane_b32 v254, s9, 5
	v_writelane_b32 v254, s10, 6
	v_writelane_b32 v254, s11, 7
	s_add_u32 s4, s0, 0x100
	s_addc_u32 s5, s1, 0
	v_writelane_b32 v254, s4, 8
	s_nop 1
	v_writelane_b32 v254, s5, 9
	s_and_b32 s4, s33, 7
	s_cmp_lg_u32 s4, 0
	s_cbranch_scc0 .LBB0_98
	v_cmp_gt_u32_e32 vcc, 2, v210
	s_and_saveexec_b64 s[4:5], vcc

.Lseam8_body:
	s_waitcnt vmcnt(0)
	v_cmp_eq_u32_e32 vcc, 0, v210
	s_waitcnt vmcnt(0) lgkmcnt(0)
	s_barrier
	s_and_saveexec_b64 s[6:7], vcc
	s_cbranch_execz .LBB0_951
	s_add_i32 s3, 0, 0x20200
	v_mov_b32_e32 v0, s3
	s_waitcnt vmcnt(0) expcnt(0) lgkmcnt(0)
	ds_read_b32 v2, v0
	s_add_i32 s3, 0, 0x20204
	v_mov_b32_e32 v0, s3
	ds_read_b32 v0, v0
	s_waitcnt lgkmcnt(1)
	v_cmp_ne_u32_e32 vcc, 0, v2
	s_cbranch_vccnz .LBB0_919
	v_readlane_b32 s8, v254, 8
	v_readlane_b32 s9, v254, 9
	s_load_dwordx2 s[12:13], s[8:9], 0x4
	s_add_u32 s8, s78, 0x1e00200
	s_addc_u32 s9, s79, 0
	s_add_u32 s10, s78, 0x1e00400
	s_addc_u32 s11, s79, 0
	s_waitcnt lgkmcnt(0)
	s_mul_i32 s3, s12, s33
	s_add_u32 s12, s78, 0x1e00500
	s_mul_i32 s3, s3, s13
	s_addc_u32 s13, s79, 0
	s_add_u32 s14, s78, 0x1e00600
	s_addc_u32 s15, s79, 0
	s_add_u32 s16, s78, 0x1e00700
	s_addc_u32 s17, s79, 0
	s_add_u32 s18, s78, 0x1e00800
	s_addc_u32 s19, s79, 0
	s_add_u32 s20, s78, 0x1e00900
	s_addc_u32 s21, s79, 0
	s_add_u32 s24, s78, 0x1e00a00
	s_addc_u32 s25, s79, 0
	s_add_u32 s26, s78, 0x1e00b00
	s_addc_u32 s27, s79, 0
	s_add_u32 s28, s78, 0x1e00c00
	s_addc_u32 s29, s79, 0
	s_add_u32 s30, s78, 0x1e00d00
	s_addc_u32 s31, s79, 0
	s_add_u32 s36, s78, 0x1e00e00
	s_addc_u32 s37, s79, 0
	s_add_u32 s38, s78, 0x1e00f00
	s_addc_u32 s39, s79, 0
	s_add_u32 s40, s78, 0x1e01000
	s_addc_u32 s41, s79, 0
	s_add_u32 s42, s78, 0x1e01100
	s_addc_u32 s43, s79, 0
	s_add_u32 s44, s78, 0x1e01200
	s_addc_u32 s45, s79, 0
	s_add_u32 s46, s78, 0x1e01300
	s_addc_u32 s47, s79, 0
	s_mov_b32 s35, 1
	v_mov_b32_e32 v16, 0
	s_branch .LBB0_907

.LBB0_952:
	s_cmp_eq_u32 s100, 9
	s_cbranch_scc1 .Lp9_stage_b
	s_mov_b32 s100, 0
	s_mov_b32 s98, s101
	s_movk_i32 s99, 0x200
	s_branch .Lp9_gate
.Lp9_stage_b:
	s_mov_b32 s100, 10
	s_cmpk_lt_u32 s101, 0x80
	s_cbranch_scc0 .Lp10a
	s_add_u32 s4, s78, 0x8000000
	s_addc_u32 s5, s79, 0
	s_add_i32 s98, s101, 0x200
	s_movk_i32 s99, 0x280
	s_branch .Lp9_body
.Lp10a:
	v_readlane_b32 s2, v254, 6
	v_readlane_b32 s3, v254, 7
	v_and_b32_e32 v0, 63, v210
	v_readfirstlane_b32 s0, v210
	v_lshlrev_b32_e32 v1, 3, v0
	v_lshlrev_b32_e32 v2, 4, v0
	v_mov_b32_e32 v3, 0x3a800000
	v_mov_b32_e32 v121, 0x358637bd
	s_lshr_b32 s0, s0, 6
	global_load_dwordx4 v[4:7], v2, s[2:3]
	global_load_dwordx4 v[8:11], v2, s[2:3] offset:1024
	global_load_dwordx4 v[12:15], v2, s[2:3] offset:2048
	global_load_dwordx4 v[16:19], v2, s[2:3] offset:3072
	s_sub_i32 s1, s101, 128
	s_lshr_b32 s4, s1, 4
	s_bfe_u32 s5, s1, 0x30001
	s_cmp_lt_u32 s4, 4
	s_cselect_b32 s4, 4, 0xff
	s_cmp_eq_u32 s5, s4
	s_cbranch_scc1 .Lp10a_done
	s_lshr_b32 s4, s1, 4
	s_mul_i32 s4, s4, 20
	s_and_b32 s5, s1, 15
	s_add_i32 s4, s4, s5
	s_lshl_b32 s4, s4, 8
	s_lshl_b32 s5, s0, 5
	s_add_i32 s4, s4, s5
	s_movk_i32 s10, 8
	s_lshl_b32 s5, s4, 11
	s_add_u32 s12, s78, s5
	s_addc_u32 s13, s79, 0
	s_add_u32 s12, s12, 0x2000000
	s_addc_u32 s13, s13, 0
	s_lshl_b32 s5, s4, 12
	s_add_u32 s14, s76, s5
	s_addc_u32 s15, s77, 0
.Lp10a_loop:
	s_add_u32 s8, s12, 0x1000
	s_addc_u32 s9, s13, 0
	global_load_dwordx2 v[20:21], v1, s[12:13] nt
	global_load_dwordx2 v[22:23], v1, s[12:13] offset:512 nt
	global_load_dwordx2 v[24:25], v1, s[12:13] offset:1024 nt
	global_load_dwordx2 v[26:27], v1, s[12:13] offset:1536 nt
	global_load_dwordx2 v[28:29], v1, s[12:13] offset:2048 nt
	global_load_dwordx2 v[30:31], v1, s[12:13] offset:2560 nt
	global_load_dwordx2 v[32:33], v1, s[12:13] offset:3072 nt
	global_load_dwordx2 v[34:35], v1, s[12:13] offset:3584 nt
	global_load_dwordx2 v[36:37], v1, s[8:9] nt
	global_load_dwordx2 v[38:39], v1, s[8:9] offset:512 nt
	global_load_dwordx2 v[40:41], v1, s[8:9] offset:1024 nt
	global_load_dwordx2 v[42:43], v1, s[8:9] offset:1536 nt
	global_load_dwordx2 v[44:45], v1, s[8:9] offset:2048 nt
	global_load_dwordx2 v[46:47], v1, s[8:9] offset:2560 nt
	global_load_dwordx2 v[48:49], v1, s[8:9] offset:3072 nt
	global_load_dwordx2 v[50:51], v1, s[8:9] offset:3584 nt
	s_waitcnt vmcnt(0)
	v_lshlrev_b32_e32 v52, 16, v20
	v_and_b32_e32 v53, 0xffff0000, v20
	v_lshlrev_b32_e32 v54, 16, v21
	v_and_b32_e32 v55, 0xffff0000, v21
	v_lshlrev_b32_e32 v56, 16, v22
	v_and_b32_e32 v57, 0xffff0000, v22
	v_lshlrev_b32_e32 v58, 16, v23
	v_and_b32_e32 v59, 0xffff0000, v23
	v_lshlrev_b32_e32 v60, 16, v24
	v_and_b32_e32 v61, 0xffff0000, v24
	v_lshlrev_b32_e32 v62, 16, v25
	v_and_b32_e32 v63, 0xffff0000, v25
	v_lshlrev_b32_e32 v64, 16, v26
	v_and_b32_e32 v65, 0xffff0000, v26
	v_lshlrev_b32_e32 v66, 16, v27
	v_and_b32_e32 v67, 0xffff0000, v27
	v_lshlrev_b32_e32 v68, 16, v28
	v_and_b32_e32 v69, 0xffff0000, v28
	v_lshlrev_b32_e32 v70, 16, v29
	v_and_b32_e32 v71, 0xffff0000, v29
	v_lshlrev_b32_e32 v72, 16, v30
	v_and_b32_e32 v73, 0xffff0000, v30
	v_lshlrev_b32_e32 v74, 16, v31
	v_and_b32_e32 v75, 0xffff0000, v31
	v_lshlrev_b32_e32 v76, 16, v32
	v_and_b32_e32 v77, 0xffff0000, v32
	v_lshlrev_b32_e32 v78, 16, v33
	v_and_b32_e32 v79, 0xffff0000, v33
	v_lshlrev_b32_e32 v80, 16, v34
	v_and_b32_e32 v81, 0xffff0000, v34
	v_lshlrev_b32_e32 v82, 16, v35
	v_and_b32_e32 v83, 0xffff0000, v35
	v_lshlrev_b32_e32 v84, 16, v36
	v_and_b32_e32 v85, 0xffff0000, v36
	v_lshlrev_b32_e32 v86, 16, v37
	v_and_b32_e32 v87, 0xffff0000, v37
	v_lshlrev_b32_e32 v88, 16, v38
	v_and_b32_e32 v89, 0xffff0000, v38
	v_lshlrev_b32_e32 v90, 16, v39
	v_and_b32_e32 v91, 0xffff0000, v39
	v_lshlrev_b32_e32 v92, 16, v40
	v_and_b32_e32 v93, 0xffff0000, v40
	v_lshlrev_b32_e32 v94, 16, v41
	v_and_b32_e32 v95, 0xffff0000, v41
	v_lshlrev_b32_e32 v96, 16, v42
	v_and_b32_e32 v97, 0xffff0000, v42
	v_lshlrev_b32_e32 v98, 16, v43
	v_and_b32_e32 v99, 0xffff0000, v43
	v_lshlrev_b32_e32 v100, 16, v44
	v_and_b32_e32 v101, 0xffff0000, v44
	v_lshlrev_b32_e32 v102, 16, v45
	v_and_b32_e32 v103, 0xffff0000, v45
	v_lshlrev_b32_e32 v104, 16, v46
	v_and_b32_e32 v105, 0xffff0000, v46
	v_lshlrev_b32_e32 v106, 16, v47
	v_and_b32_e32 v107, 0xffff0000, v47
	v_lshlrev_b32_e32 v108, 16, v48
	v_and_b32_e32 v109, 0xffff0000, v48
	v_lshlrev_b32_e32 v110, 16, v49
	v_and_b32_e32 v111, 0xffff0000, v49
	v_lshlrev_b32_e32 v112, 16, v50
	v_and_b32_e32 v113, 0xffff0000, v50
	v_lshlrev_b32_e32 v114, 16, v51
	v_and_b32_e32 v115, 0xffff0000, v51
	v_mul_f32_e32 v116, v52, v52
	v_mul_f32_e32 v117, v68, v68
	v_mul_f32_e32 v118, v84, v84
	v_mul_f32_e32 v119, v100, v100
	v_fmac_f32_e32 v116, v53, v53
	v_fmac_f32_e32 v117, v69, v69
	v_fmac_f32_e32 v118, v85, v85
	v_fmac_f32_e32 v119, v101, v101
	v_fmac_f32_e32 v116, v54, v54
	v_fmac_f32_e32 v117, v70, v70
	v_fmac_f32_e32 v118, v86, v86
	v_fmac_f32_e32 v119, v102, v102
	v_fmac_f32_e32 v116, v55, v55
	v_fmac_f32_e32 v117, v71, v71
	v_fmac_f32_e32 v118, v87, v87
	v_fmac_f32_e32 v119, v103, v103
	v_fmac_f32_e32 v116, v56, v56
	v_fmac_f32_e32 v117, v72, v72
	v_fmac_f32_e32 v118, v88, v88
	v_fmac_f32_e32 v119, v104, v104
	v_fmac_f32_e32 v116, v57, v57
	v_fmac_f32_e32 v117, v73, v73
	v_fmac_f32_e32 v118, v89, v89
	v_fmac_f32_e32 v119, v105, v105
	v_fmac_f32_e32 v116, v58, v58
	v_fmac_f32_e32 v117, v74, v74
	v_fmac_f32_e32 v118, v90, v90
	v_fmac_f32_e32 v119, v106, v106
	v_fmac_f32_e32 v116, v59, v59
	v_fmac_f32_e32 v117, v75, v75
	v_fmac_f32_e32 v118, v91, v91
	v_fmac_f32_e32 v119, v107, v107
	v_fmac_f32_e32 v116, v60, v60
	v_fmac_f32_e32 v117, v76, v76
	v_fmac_f32_e32 v118, v92, v92
	v_fmac_f32_e32 v119, v108, v108
	v_fmac_f32_e32 v116, v61, v61
	v_fmac_f32_e32 v117, v77, v77
	v_fmac_f32_e32 v118, v93, v93
	v_fmac_f32_e32 v119, v109, v109
	v_fmac_f32_e32 v116, v62, v62
	v_fmac_f32_e32 v117, v78, v78
	v_fmac_f32_e32 v118, v94, v94
	v_fmac_f32_e32 v119, v110, v110
	v_fmac_f32_e32 v116, v63, v63
	v_fmac_f32_e32 v117, v79, v79
	v_fmac_f32_e32 v118, v95, v95
	v_fmac_f32_e32 v119, v111, v111
	v_fmac_f32_e32 v116, v64, v64
	v_fmac_f32_e32 v117, v80, v80
	v_fmac_f32_e32 v118, v96, v96
	v_fmac_f32_e32 v119, v112, v112
	v_fmac_f32_e32 v116, v65, v65
	v_fmac_f32_e32 v117, v81, v81
	v_fmac_f32_e32 v118, v97, v97
	v_fmac_f32_e32 v119, v113, v113
	v_fmac_f32_e32 v116, v66, v66
	v_fmac_f32_e32 v117, v82, v82
	v_fmac_f32_e32 v118, v98, v98
	v_fmac_f32_e32 v119, v114, v114
	v_fmac_f32_e32 v116, v67, v67
	v_fmac_f32_e32 v117, v83, v83
	v_fmac_f32_e32 v118, v99, v99
	v_fmac_f32_e32 v119, v115, v115
	v_add_f32_dpp v132, v116, v116 quad_perm:[1,0,3,2] row_mask:0xf bank_mask:0xf
	v_add_f32_dpp v133, v117, v117 quad_perm:[1,0,3,2] row_mask:0xf bank_mask:0xf
	v_add_f32_dpp v134, v118, v118 quad_perm:[1,0,3,2] row_mask:0xf bank_mask:0xf
	v_add_f32_dpp v135, v119, v119 quad_perm:[1,0,3,2] row_mask:0xf bank_mask:0xf
	v_add_f32_dpp v136, v132, v132 quad_perm:[2,3,0,1] row_mask:0xf bank_mask:0xf
	v_add_f32_dpp v137, v133, v133 quad_perm:[2,3,0,1] row_mask:0xf bank_mask:0xf
	v_add_f32_dpp v138, v134, v134 quad_perm:[2,3,0,1] row_mask:0xf bank_mask:0xf
	v_add_f32_dpp v139, v135, v135 quad_perm:[2,3,0,1] row_mask:0xf bank_mask:0xf
	v_add_f32_dpp v132, v136, v136 row_ror:4 row_mask:0xf bank_mask:0xf
	v_add_f32_dpp v133, v137, v137 row_ror:4 row_mask:0xf bank_mask:0xf
	v_add_f32_dpp v134, v138, v138 row_ror:4 row_mask:0xf bank_mask:0xf
	v_add_f32_dpp v135, v139, v139 row_ror:4 row_mask:0xf bank_mask:0xf
	v_add_f32_dpp v136, v132, v132 row_ror:8 row_mask:0xf bank_mask:0xf
	v_add_f32_dpp v137, v133, v133 row_ror:8 row_mask:0xf bank_mask:0xf
	v_add_f32_dpp v138, v134, v134 row_ror:8 row_mask:0xf bank_mask:0xf
	v_add_f32_dpp v139, v135, v135 row_ror:8 row_mask:0xf bank_mask:0xf
	s_nop 1
	v_readlane_b32 s16, v136, 0
	v_readlane_b32 s17, v136, 16
	v_readlane_b32 s18, v136, 32
	v_readlane_b32 s19, v136, 48
	v_readlane_b32 s20, v137, 0
	v_readlane_b32 s21, v137, 16
	v_readlane_b32 s22, v137, 32
	v_readlane_b32 s23, v137, 48
	v_readlane_b32 s24, v138, 0
	v_readlane_b32 s25, v138, 16
	v_readlane_b32 s26, v138, 32
	v_readlane_b32 s27, v138, 48
	v_readlane_b32 s28, v139, 0
	v_readlane_b32 s29, v139, 16
	v_readlane_b32 s30, v139, 32
	v_readlane_b32 s31, v139, 48
	s_nop 1
	v_mov_b32_e32 v132, s16
	v_mov_b32_e32 v133, s20
	v_mov_b32_e32 v134, s24
	v_mov_b32_e32 v135, s28
	v_add_f32_e32 v132, s17, v132
	v_add_f32_e32 v133, s21, v133
	v_add_f32_e32 v134, s25, v134
	v_add_f32_e32 v135, s29, v135
	v_add_f32_e32 v132, s18, v132
	v_add_f32_e32 v133, s22, v133
	v_add_f32_e32 v134, s26, v134
	v_add_f32_e32 v135, s30, v135
	v_add_f32_e32 v132, s19, v132
	v_add_f32_e32 v133, s23, v133
	v_add_f32_e32 v134, s27, v134
	v_add_f32_e32 v135, s31, v135
	v_fma_f32 v140, v132, v3, v121
	v_fma_f32 v141, v133, v3, v121
	v_fma_f32 v142, v134, v3, v121
	v_fma_f32 v143, v135, v3, v121
	v_rsq_f32_e32 v124, v140
	v_rsq_f32_e32 v126, v141
	v_rsq_f32_e32 v128, v142
	v_rsq_f32_e32 v130, v143
	s_nop 0
	v_mul_f32_e32 v132, v140, v124
	v_mul_f32_e32 v133, v141, v126
	v_mul_f32_e32 v134, v142, v128
	v_mul_f32_e32 v135, v143, v130
	v_mul_f32_e32 v132, v132, v124
	v_mul_f32_e32 v133, v133, v126
	v_mul_f32_e32 v134, v134, v128
	v_mul_f32_e32 v135, v135, v130
	v_sub_f32_e32 v132, 1.0, v132
	v_sub_f32_e32 v133, 1.0, v133
	v_sub_f32_e32 v134, 1.0, v134
	v_sub_f32_e32 v135, 1.0, v135
	v_mul_f32_e32 v136, 0.5, v124
	v_mul_f32_e32 v137, 0.5, v126
	v_mul_f32_e32 v138, 0.5, v128
	v_mul_f32_e32 v139, 0.5, v130
	v_fmac_f32_e32 v124, v136, v132
	v_fmac_f32_e32 v126, v137, v133
	v_fmac_f32_e32 v128, v138, v134
	v_fmac_f32_e32 v130, v139, v135
	v_pk_mul_f32 v[52:53], v[52:53], v[124:125] op_sel_hi:[1,0]
	v_pk_mul_f32 v[54:55], v[54:55], v[124:125] op_sel_hi:[1,0]
	v_pk_mul_f32 v[56:57], v[56:57], v[124:125] op_sel_hi:[1,0]
	v_pk_mul_f32 v[58:59], v[58:59], v[124:125] op_sel_hi:[1,0]
	v_pk_mul_f32 v[60:61], v[60:61], v[124:125] op_sel_hi:[1,0]
	v_pk_mul_f32 v[62:63], v[62:63], v[124:125] op_sel_hi:[1,0]
	v_pk_mul_f32 v[64:65], v[64:65], v[124:125] op_sel_hi:[1,0]
	v_pk_mul_f32 v[66:67], v[66:67], v[124:125] op_sel_hi:[1,0]
	v_pk_mul_f32 v[52:53], v[52:53], v[4:5]
	v_pk_mul_f32 v[54:55], v[54:55], v[6:7]
	v_pk_mul_f32 v[56:57], v[56:57], v[8:9]
	v_pk_mul_f32 v[58:59], v[58:59], v[10:11]
	v_pk_mul_f32 v[60:61], v[60:61], v[12:13]
	v_pk_mul_f32 v[62:63], v[62:63], v[14:15]
	v_pk_mul_f32 v[64:65], v[64:65], v[16:17]
	v_pk_mul_f32 v[66:67], v[66:67], v[18:19]
	global_store_dwordx4 v2, v[52:55], s[14:15] nt
	global_store_dwordx4 v2, v[56:59], s[14:15] offset:1024 nt
	global_store_dwordx4 v2, v[60:63], s[14:15] offset:2048 nt
	global_store_dwordx4 v2, v[64:67], s[14:15] offset:3072 nt
	v_pk_mul_f32 v[68:69], v[68:69], v[126:127] op_sel_hi:[1,0]
	v_pk_mul_f32 v[70:71], v[70:71], v[126:127] op_sel_hi:[1,0]
	v_pk_mul_f32 v[72:73], v[72:73], v[126:127] op_sel_hi:[1,0]
	v_pk_mul_f32 v[74:75], v[74:75], v[126:127] op_sel_hi:[1,0]
	v_pk_mul_f32 v[76:77], v[76:77], v[126:127] op_sel_hi:[1,0]
	v_pk_mul_f32 v[78:79], v[78:79], v[126:127] op_sel_hi:[1,0]
	v_pk_mul_f32 v[80:81], v[80:81], v[126:127] op_sel_hi:[1,0]
	v_pk_mul_f32 v[82:83], v[82:83], v[126:127] op_sel_hi:[1,0]
	v_pk_mul_f32 v[68:69], v[68:69], v[4:5]
	v_pk_mul_f32 v[70:71], v[70:71], v[6:7]
	v_pk_mul_f32 v[72:73], v[72:73], v[8:9]
	v_pk_mul_f32 v[74:75], v[74:75], v[10:11]
	v_pk_mul_f32 v[76:77], v[76:77], v[12:13]
	v_pk_mul_f32 v[78:79], v[78:79], v[14:15]
	v_pk_mul_f32 v[80:81], v[80:81], v[16:17]
	v_pk_mul_f32 v[82:83], v[82:83], v[18:19]
	s_add_u32 s2, s14, 0x1000
	s_addc_u32 s3, s15, 0
	global_store_dwordx4 v2, v[68:71], s[2:3] nt
	global_store_dwordx4 v2, v[72:75], s[2:3] offset:1024 nt
	global_store_dwordx4 v2, v[76:79], s[2:3] offset:2048 nt
	global_store_dwordx4 v2, v[80:83], s[2:3] offset:3072 nt
	v_pk_mul_f32 v[84:85], v[84:85], v[128:129] op_sel_hi:[1,0]
	v_pk_mul_f32 v[86:87], v[86:87], v[128:129] op_sel_hi:[1,0]
	v_pk_mul_f32 v[88:89], v[88:89], v[128:129] op_sel_hi:[1,0]
	v_pk_mul_f32 v[90:91], v[90:91], v[128:129] op_sel_hi:[1,0]
	v_pk_mul_f32 v[92:93], v[92:93], v[128:129] op_sel_hi:[1,0]
	v_pk_mul_f32 v[94:95], v[94:95], v[128:129] op_sel_hi:[1,0]
	v_pk_mul_f32 v[96:97], v[96:97], v[128:129] op_sel_hi:[1,0]
	v_pk_mul_f32 v[98:99], v[98:99], v[128:129] op_sel_hi:[1,0]
	v_pk_mul_f32 v[84:85], v[84:85], v[4:5]
	v_pk_mul_f32 v[86:87], v[86:87], v[6:7]
	v_pk_mul_f32 v[88:89], v[88:89], v[8:9]
	v_pk_mul_f32 v[90:91], v[90:91], v[10:11]
	v_pk_mul_f32 v[92:93], v[92:93], v[12:13]
	v_pk_mul_f32 v[94:95], v[94:95], v[14:15]
	v_pk_mul_f32 v[96:97], v[96:97], v[16:17]
	v_pk_mul_f32 v[98:99], v[98:99], v[18:19]
	s_add_u32 s2, s14, 0x2000
	s_addc_u32 s3, s15, 0
	global_store_dwordx4 v2, v[84:87], s[2:3] nt
	global_store_dwordx4 v2, v[88:91], s[2:3] offset:1024 nt
	global_store_dwordx4 v2, v[92:95], s[2:3] offset:2048 nt
	global_store_dwordx4 v2, v[96:99], s[2:3] offset:3072 nt
	v_pk_mul_f32 v[100:101], v[100:101], v[130:131] op_sel_hi:[1,0]
	v_pk_mul_f32 v[102:103], v[102:103], v[130:131] op_sel_hi:[1,0]
	v_pk_mul_f32 v[104:105], v[104:105], v[130:131] op_sel_hi:[1,0]
	v_pk_mul_f32 v[106:107], v[106:107], v[130:131] op_sel_hi:[1,0]
	v_pk_mul_f32 v[108:109], v[108:109], v[130:131] op_sel_hi:[1,0]
	v_pk_mul_f32 v[110:111], v[110:111], v[130:131] op_sel_hi:[1,0]
	v_pk_mul_f32 v[112:113], v[112:113], v[130:131] op_sel_hi:[1,0]
	v_pk_mul_f32 v[114:115], v[114:115], v[130:131] op_sel_hi:[1,0]
	v_pk_mul_f32 v[100:101], v[100:101], v[4:5]
	v_pk_mul_f32 v[102:103], v[102:103], v[6:7]
	v_pk_mul_f32 v[104:105], v[104:105], v[8:9]
	v_pk_mul_f32 v[106:107], v[106:107], v[10:11]
	v_pk_mul_f32 v[108:109], v[108:109], v[12:13]
	v_pk_mul_f32 v[110:111], v[110:111], v[14:15]
	v_pk_mul_f32 v[112:113], v[112:113], v[16:17]
	v_pk_mul_f32 v[114:115], v[114:115], v[18:19]
	s_add_u32 s2, s14, 0x3000
	s_addc_u32 s3, s15, 0
	global_store_dwordx4 v2, v[100:103], s[2:3] nt
	global_store_dwordx4 v2, v[104:107], s[2:3] offset:1024 nt
	global_store_dwordx4 v2, v[108:111], s[2:3] offset:2048 nt
	global_store_dwordx4 v2, v[112:115], s[2:3] offset:3072 nt
	s_add_u32 s12, s12, 0x2000
	s_addc_u32 s13, s13, 0
	s_add_u32 s14, s14, 0x4000
	s_addc_u32 s15, s15, 0
	s_add_i32 s10, s10, -1
	s_cmp_lg_u32 s10, 0
	s_cbranch_scc1 .Lp10a_loop
.Lp10a_done:
	s_branch .LBB0_969

.Lp9_body:
	s_cmp_ge_i32 s98, s99
	v_readfirstlane_b32 s14, v210
	s_cbranch_scc1 .LBB0_969
	v_lshlrev_b32_e32 v1, 4, v210
	v_add_u32_e32 v8, 0x2000, v1
	v_lshrrev_b32_e32 v2, 7, v8
	v_bfe_u32 v11, v210, 2, 4
	s_movk_i32 s0, 0xf0
	v_lshrrev_b32_e32 v0, 3, v210
	v_and_or_b32 v2, v2, s0, v11
	s_movk_i32 s0, 0x70
	s_ashr_i32 s35, s98, 31
	v_and_or_b32 v0, v0, s0, v11
	s_lshr_b32 s0, s35, 29
	s_add_i32 s0, s98, s0
	s_lshr_b32 s8, s14, 6
	s_ashr_i32 s9, s0, 3
	s_and_b32 s0, s0, -8
	s_lshr_b32 s1, s14, 8
	s_lshl_b32 s3, s8, 10
	s_sub_i32 s0, s98, s0
	s_cmp_lt_i32 s0, 0
	s_movk_i32 s40, 0x51
	s_cselect_b32 s10, s40, 0x50
	s_mul_i32 s0, s0, s10
	s_add_i32 s0, s0, s9
	s_ashr_i32 s9, s0, 31
	s_lshr_b32 s9, s9, 28
	s_add_i32 s9, s0, s9
	s_ashr_i32 s10, s9, 4
	s_and_b32 s9, s9, 0xfff0
	s_sub_i32 s9, s0, s9
	s_bfe_i32 s0, s9, 0x80000
	s_bfe_u32 s0, s0, 0x2000d
	s_add_i32 s11, s9, s0
	s_bfe_i32 s0, s11, 0x80000
	s_and_b32 s11, s11, 0xfc
	s_sub_i32 s9, s9, s11
	s_lshl_b32 s10, s10, 2
	s_sext_i32_i16 s0, s0
	s_sext_i32_i8 s9, s9
	s_lshr_b32 s0, s0, 2
	s_add_i32 s28, s10, s9
	s_ashr_i32 s29, s28, 31
	s_bfe_i64 s[12:13], s[0:1], 0x100000
	v_and_b32_e32 v3, 32, v210
	s_lshl_b64 s[10:11], s[28:29], 21
	s_lshl_b64 s[12:13], s[12:13], 21
	v_bitop3_b32 v9, v1, v3, 48 bitop3:0x6c
	s_waitcnt lgkmcnt(0)
	v_and_b32_e32 v10, 64, v210
	s_add_u32 s36, s74, s12
	v_or_b32_e32 v1, v9, v10
	s_addc_u32 s37, s75, s13
	s_add_i32 s29, s3, 0
	v_lshl_or_b32 v146, v0, 13, v1
	s_add_i32 m0, s29, 0x10000
	v_lshl_or_b32 v144, v2, 13, v1
	global_load_lds_dwordx4 v146, s[36:37]
	s_add_i32 m0, s29, 0x12000
	s_add_u32 s12, s36, 0x100000
	global_load_lds_dwordx4 v144, s[36:37]
	s_addc_u32 s13, s37, 0
	s_add_i32 m0, s29, 0x14000
	v_mov_b32_e32 v147, 0
	global_load_lds_dwordx4 v146, s[12:13]
	s_add_i32 m0, s29, 0x16000
	s_add_u32 s30, s4, s10
	s_addc_u32 s31, s5, s11
	s_add_i32 s41, s29, 0x2000
	global_load_lds_dwordx4 v144, s[12:13]
	s_mov_b32 m0, s29
	s_add_u32 s10, s30, 0x100000
	global_load_lds_dwordx4 v146, s[30:31]
	s_mov_b32 m0, s41
	s_addc_u32 s11, s31, 0
	s_add_i32 s42, s29, 0x4000
	global_load_lds_dwordx4 v144, s[30:31]
	s_mov_b32 m0, s42
	s_add_i32 s43, s29, 0x6000
	global_load_lds_dwordx4 v146, s[10:11]
	s_mov_b32 m0, s43
	v_mov_b32_e32 v145, v147
	global_load_lds_dwordx4 v144, s[10:11]
	s_cmp_eq_u32 s1, 1
	s_mov_b32 s9, 0
	s_mov_b32 s44, 0x10000
	v_lshl_add_u64 v[6:7], s[36:37], 0, v[146:147]
	v_lshl_add_u64 v[4:5], s[36:37], 0, v[144:145]
	s_mov_b32 s45, 0x14000
	v_lshl_add_u64 v[2:3], s[30:31], 0, v[146:147]
	v_lshl_add_u64 v[0:1], s[30:31], 0, v[144:145]
	s_cselect_b64 s[10:11], -1, 0
	s_cmp_lg_u32 s1, 1
	s_movk_i32 s46, 0x4000
	s_cbranch_scc1 .LBB0_956
	s_barrier
.LBB0_956:
	s_mov_b64 s[12:13], 0x80
	s_and_b32 s18, s8, 3
	s_add_i32 m0, s29, 0x18000
	v_lshl_add_u64 v[6:7], v[6:7], 0, s[12:13]
	s_lshl_b32 s15, s1, 13
	s_lshl_b32 s19, s18, 12
	s_waitcnt vmcnt(2)
	s_barrier
	global_load_lds_dwordx4 v[6:7], off
	v_lshl_add_u64 v[4:5], v[4:5], 0, s[12:13]
	s_add_i32 m0, s29, 0x1a000
	s_add_i32 s47, s29, 0x8000
	s_add_i32 s48, s29, 0xa000
	global_load_lds_dwordx4 v[4:5], off
	v_lshl_add_u64 v[2:3], v[2:3], 0, s[12:13]
	s_mov_b32 m0, s47
	s_add_u32 s16, s36, 0x100080
	global_load_lds_dwordx4 v[2:3], off
	v_lshl_add_u64 v[0:1], v[0:1], 0, s[12:13]
	s_mov_b32 m0, s48
	s_addc_u32 s17, s37, 0
	global_load_lds_dwordx4 v[0:1], off
	s_add_i32 m0, s29, 0x1c000
	v_lshl_add_u64 v[0:1], s[16:17], 0, v[146:147]
	global_load_lds_dwordx4 v[0:1], off
	v_lshl_add_u64 v[0:1], s[16:17], 0, v[144:145]
	s_add_i32 m0, s29, 0x1e000
	v_lshlrev_b32_e32 v4, 2, v210
	global_load_lds_dwordx4 v[0:1], off
	v_bfe_u32 v1, v210, 4, 2
	v_and_b32_e32 v0, 15, v210
	v_lshlrev_b32_e32 v2, 4, v1
	v_lshl_or_b32 v3, v0, 6, v2
	v_and_b32_e32 v4, 32, v4
	s_cmpk_lt_u32 s14, 0x100
	s_sext_i32_i8 s8, s0
	v_bitop3_b32 v3, v3, s15, v4 bitop3:0xde
	v_lshlrev_b32_e32 v5, 6, v210
	s_movk_i32 s0, 0x3c0
	s_cselect_b64 s[14:15], -1, 0
	s_lshl_b32 s16, s1, 2
	v_and_or_b32 v5, v5, s0, v2
	s_or_b32 s16, s16, s18
	v_bitop3_b32 v149, s19, v5, v4 bitop3:0xf6
	s_lshl_b32 s0, s18, 6
	s_mulk_i32 s16, 0x900
	v_and_b32_e32 v4, 7, v210
	v_lshl_or_b32 v162, v1, 3, s0
	v_lshl_or_b32 v148, v4, 3, s0
	s_add_i32 s0, s16, 0
	v_bfe_u32 v1, v210, 3, 3
	s_add_i32 s0, s0, 0x20400
	v_lshlrev_b32_e32 v5, 4, v4
	v_lshl_or_b32 v163, s1, 6, v1
	s_movk_i32 s1, 0x90
	v_mov_b32_e32 v4, s0
	v_mad_u32_u24 v0, v0, s1, v4
	v_mad_u32_u24 v1, v1, s1, v4
	v_lshlrev_b32_e32 v4, 10, v210
	v_and_b32_e32 v4, 0xe0000, v4
	v_lshlrev_b32_e32 v6, 13, v11
	v_or3_b32 v4, v9, v4, v6
	v_add_u32_e32 v150, v4, v10
	v_lshlrev_b32_e32 v4, 6, v8
	s_waitcnt vmcnt(6)
	v_and_b32_e32 v4, 0x1e0000, v4
	v_or3_b32 v4, v9, v4, v6
	s_add_i32 s53, 0, 0x10000
	s_add_i32 s54, 0, 0x14000
	s_mov_b32 s49, 0x18000
	s_mov_b32 s50, 0x8000
	s_mov_b32 s51, 0x1c000
	s_ashr_i32 s52, s33, 31
	v_mov_b32_e32 v151, v147
	v_add_u32_e32 v152, v4, v10
	v_mov_b32_e32 v153, v147
	v_mov_b32_e32 v154, s99
	v_mov_b32_e32 v155, 0
	v_add_u32_e32 v156, -1, v154
	v_mov_b32_e32 v157, 0
	v_add_u32_e32 v164, s53, v149
	v_add_u32_e32 v165, s54, v149
	v_add_u32_e32 v166, 0, v3
	s_mov_b32 s55, 0xc000
	s_mov_b64 s[16:17], 0x5000
	s_movk_i32 s56, 0x5000
	v_add_u32_e32 v167, v0, v2
	v_add_u32_e32 v168, v1, v5
	s_mov_b32 s57, 0x40000
	s_mov_b32 s58, 0x44000
	s_mov_b32 s59, 0x48000
	s_mov_b32 s60, 0x4c000
	s_mov_b32 s61, 0x50000
	s_mov_b32 s62, 0x54000
	s_mov_b32 s63, 0x58000
	s_mov_b32 s64, 0x5c000
	s_mov_b32 s65, 0
	s_barrier
	s_branch .LBB0_959

.LBB0_959:
	s_add_i32 s65, s65, 1
	s_mul_i32 s0, s65, s52
	s_mul_hi_u32 s1, s65, s33
	s_add_i32 s1, s1, s0
	s_mul_i32 s0, s65, s33
	s_add_u32 s24, s0, s98
	s_addc_u32 s25, s1, s35
	v_cmp_gt_i64_e32 vcc, s[24:25], v[156:157]
	v_cmp_lt_i64_e64 s[0:1], s[24:25], v[154:155]
	s_cbranch_vccnz .LBB0_961
	s_ashr_i32 s18, s24, 31
	s_lshr_b32 s18, s18, 29
	s_add_i32 s18, s24, s18
	s_ashr_i32 s19, s18, 3
	s_and_b32 s18, s18, -8
	s_sub_i32 s18, s24, s18
	s_cmp_lt_i32 s18, 0
	s_cselect_b32 s20, s40, 0x50
	s_mul_i32 s18, s18, s20
	s_add_i32 s18, s18, s19
	s_ashr_i32 s19, s18, 31
	s_lshr_b32 s19, s19, 28
	s_add_i32 s19, s18, s19
	s_ashr_i32 s20, s19, 4
	s_lshl_b32 s20, s20, 2
	s_sub_i32 s21, 0xa0, s20
	s_min_i32 s21, s21, 4
	s_abs_i32 s24, s21
	v_cvt_f32_u32_e32 v0, s24
	s_sub_i32 s26, 0, s24
	s_and_b32 s19, s19, -16
	s_sub_i32 s19, s18, s19
	v_rcp_iflag_f32_e32 v0, v0
	s_abs_i32 s18, s19
	s_xor_b32 s25, s19, s21
	s_ashr_i32 s25, s25, 31
	v_mul_f32_e32 v0, 0x4f7ffffe, v0
	v_cvt_u32_f32_e32 v0, v0
	s_nop 0
	v_readfirstlane_b32 s27, v0
	s_mul_i32 s26, s26, s27
	s_mul_hi_u32 s26, s27, s26
	s_add_i32 s27, s27, s26
	s_mul_hi_u32 s26, s18, s27
	s_mul_i32 s27, s26, s24
	s_sub_i32 s18, s18, s27
	s_add_i32 s38, s26, 1
	s_sub_i32 s27, s18, s24
	s_cmp_ge_u32 s18, s24
	s_cselect_b32 s26, s38, s26
	s_cselect_b32 s18, s27, s18
	s_add_i32 s27, s26, 1
	s_cmp_ge_u32 s18, s24
	s_cselect_b32 s18, s27, s26
	s_xor_b32 s18, s18, s25
	s_sub_i32 s18, s18, s25
	s_mul_i32 s21, s18, s21
	s_sub_i32 s19, s19, s21
	s_add_i32 s20, s20, s19

.LBB0_969:
	s_cmp_eq_u32 s100, 0
	s_cbranch_scc0 .Lp9_to_seam9
	s_mov_b32 s100, 9
	s_branch .Lseam8_body

.LBB0_1019:
	v_readlane_b32 s2, v254, 6
	v_readlane_b32 s3, v254, 7
	v_and_b32_e32 v0, 63, v210
	v_readfirstlane_b32 s0, v210
	v_lshlrev_b32_e32 v1, 3, v0
	v_lshlrev_b32_e32 v2, 4, v0
	v_mov_b32_e32 v3, 0x3a800000
	v_mov_b32_e32 v121, 0x358637bd
	s_lshr_b32 s0, s0, 6
	global_load_dwordx4 v[4:7], v2, s[2:3]
	global_load_dwordx4 v[8:11], v2, s[2:3] offset:1024
	global_load_dwordx4 v[12:15], v2, s[2:3] offset:2048
	global_load_dwordx4 v[16:19], v2, s[2:3] offset:3072
	s_lshr_b32 s1, s101, 3
	s_lshr_b32 s4, s1, 2
	s_mul_i32 s4, s4, 20
	s_and_b32 s5, s1, 3
	s_add_i32 s4, s4, s5
	s_add_i32 s4, s4, 16
	s_lshl_b32 s4, s4, 8
	s_and_b32 s5, s101, 7
	s_lshl_b32 s5, s5, 3
	s_add_i32 s5, s5, s0
	s_lshl_b32 s5, s5, 2
	s_add_i32 s4, s4, s5
	s_movk_i32 s10, 1
	s_lshl_b32 s5, s4, 11
	s_add_u32 s12, s78, s5
	s_addc_u32 s13, s79, 0
	s_add_u32 s12, s12, 0x2000000
	s_addc_u32 s13, s13, 0
	s_lshl_b32 s5, s4, 12
	s_add_u32 s14, s76, s5
	s_addc_u32 s15, s77, 0

.Lp10b_done:
	v_readlane_b32 s2, v254, 6
	v_readlane_b32 s3, v254, 7
	v_and_b32_e32 v0, 63, v210
	v_readfirstlane_b32 s0, v210
	v_lshlrev_b32_e32 v1, 3, v0
	v_lshlrev_b32_e32 v2, 4, v0
	v_mov_b32_e32 v3, 0x3a800000
	v_mov_b32_e32 v121, 0x358637bd
	s_lshr_b32 s0, s0, 6
	global_load_dwordx4 v[4:7], v2, s[2:3]
	global_load_dwordx4 v[8:11], v2, s[2:3] offset:1024
	global_load_dwordx4 v[12:15], v2, s[2:3] offset:2048
	global_load_dwordx4 v[16:19], v2, s[2:3] offset:3072
	s_cmpk_gt_u32 s101, 63
	s_cbranch_scc1 .Lp10c_done
	s_lshr_b32 s1, s101, 3
	s_lshr_b32 s4, s1, 1
	s_mul_i32 s4, s4, 20
	s_and_b32 s5, s1, 1
	s_add_i32 s4, s4, s5
	s_add_i32 s4, s4, 8
	s_lshl_b32 s4, s4, 8
	s_and_b32 s5, s101, 7
	s_lshl_b32 s5, s5, 3
	s_add_i32 s5, s5, s0
	s_lshl_b32 s5, s5, 2
	s_add_i32 s4, s4, s5
	s_movk_i32 s10, 1
	s_lshl_b32 s5, s4, 11
	s_add_u32 s12, s78, s5
	s_addc_u32 s13, s79, 0
	s_add_u32 s12, s12, 0x2000000
	s_addc_u32 s13, s13, 0
	s_lshl_b32 s5, s4, 12
	s_add_u32 s14, s76, s5
	s_addc_u32 s15, s77, 0

.Lp10c_done:
.LBB0_1022:
	s_endpgm

	.amdhsa_kernel _ZN2pb8mega_fwdENS_4ArgsE
		.amdhsa_group_segment_fixed_size 0
		.amdhsa_private_segment_fixed_size 0
		.amdhsa_kernarg_size 512
		.amdhsa_user_sgpr_count 2
		.amdhsa_user_sgpr_dispatch_ptr 0
		.amdhsa_user_sgpr_queue_ptr 0
		.amdhsa_user_sgpr_kernarg_segment_ptr 1
		.amdhsa_user_sgpr_dispatch_id 0
		.amdhsa_user_sgpr_kernarg_preload_length 0
		.amdhsa_user_sgpr_kernarg_preload_offset 0
		.amdhsa_user_sgpr_private_segment_size 0
		.amdhsa_uses_dynamic_stack 0
		.amdhsa_enable_private_segment 0
		.amdhsa_system_sgpr_workgroup_id_x 1
		.amdhsa_system_sgpr_workgroup_id_y 0
		.amdhsa_system_sgpr_workgroup_id_z 0
		.amdhsa_system_sgpr_workgroup_info 0
		.amdhsa_system_vgpr_workitem_id 2
		.amdhsa_next_free_vgpr 255
		.amdhsa_next_free_sgpr 102
		.amdhsa_accum_offset 256
		.amdhsa_reserve_vcc 1
		.amdhsa_float_round_mode_32 0
		.amdhsa_float_round_mode_16_64 0
		.amdhsa_float_denorm_mode_32 3
		.amdhsa_float_denorm_mode_16_64 3
		.amdhsa_dx10_clamp 1
		.amdhsa_ieee_mode 1
		.amdhsa_fp16_overflow 0
		.amdhsa_tg_split 0
		.amdhsa_exception_fp_ieee_invalid_op 0
		.amdhsa_exception_fp_denorm_src 0
		.amdhsa_exception_fp_ieee_div_zero 0
		.amdhsa_exception_fp_ieee_overflow 0
		.amdhsa_exception_fp_ieee_underflow 0
		.amdhsa_exception_fp_ieee_inexact 0
		.amdhsa_exception_int_div_zero 0
	.end_amdhsa_kernel

amdhsa.kernels:
  - .agpr_count:     0
    .args:
      - .offset:         0
        .size:           256
        .value_kind:     by_value
      - .offset:         256
        .size:           4
        .value_kind:     hidden_block_count_x
      - .offset:         260
        .size:           4
        .value_kind:     hidden_block_count_y
      - .offset:         264
        .size:           4
        .value_kind:     hidden_block_count_z
      - .offset:         268
        .size:           2
        .value_kind:     hidden_group_size_x
      - .offset:         270
        .size:           2
        .value_kind:     hidden_group_size_y
      - .offset:         272
        .size:           2
        .value_kind:     hidden_group_size_z
      - .offset:         274
        .size:           2
        .value_kind:     hidden_remainder_x
      - .offset:         276
        .size:           2
        .value_kind:     hidden_remainder_y
      - .offset:         278
        .size:           2
        .value_kind:     hidden_remainder_z
      - .offset:         296
        .size:           8
        .value_kind:     hidden_global_offset_x
      - .offset:         304
        .size:           8
        .value_kind:     hidden_global_offset_y
      - .offset:         312
        .size:           8
        .value_kind:     hidden_global_offset_z
      - .offset:         320
        .size:           2
        .value_kind:     hidden_grid_dims
      - .offset:         344
        .size:           8
        .value_kind:     hidden_multigrid_sync_arg
      - .offset:         376
        .size:           4
        .value_kind:     hidden_dynamic_lds_size
    .group_segment_fixed_size: 0
    .kernarg_segment_align: 8
    .kernarg_segment_size: 512
    .language:       OpenCL C
    .language_version:
      - 2
      - 0
    .max_flat_workgroup_size: 512
    .name:           _ZN2pb8mega_fwdENS_4ArgsE
    .private_segment_fixed_size: 0
    .sgpr_count:     108
    .sgpr_spill_count: 74
    .symbol:         _ZN2pb8mega_fwdENS_4ArgsE.kd
    .uniform_work_group_size: 1
    .uses_dynamic_stack: false
    .vgpr_count:     255
    .vgpr_spill_count: 0
    .wavefront_size: 64
